# class-balanced conversion share: workgroups 64..191 take 6 MLP1-L1 conversion tiles each after their gate columns (cmp phase)
# speedup vs baseline: 1.0052x; 1.0052x over previous
.LBB0_690:
	s_load_dwordx4 s[4:7], s[0:1], 0x78
	s_waitcnt lgkmcnt(0)
	v_writelane_b32 v232, s4, 21
	v_writelane_b32 v232, s5, 22
	v_writelane_b32 v232, s6, 23
	v_writelane_b32 v232, s7, 24
	v_mov_b32_e32 v0, v136
	s_and_b64 vcc, exec, s[10:11]
	s_cbranch_vccnz .LBB0_702
	s_load_dwordx4 s[4:7], s[0:1], 0x78
	v_ashrrev_i32_e32 v9, 3, v0
	v_lshlrev_b32_e32 v0, 3, v0
	v_and_b32_e32 v8, 56, v0
	v_lshl_add_u32 v2, v9, 2, 16
	s_waitcnt lgkmcnt(0)
	s_add_u32 s16, s6, 0x4000000
	s_addc_u32 s17, s7, 0
	s_add_u32 s18, s4, 0x2000
	s_addc_u32 s19, s5, 0
	s_add_u32 s20, s52, 0x2800000
	s_addc_u32 s21, s53, 0
	s_cmp_lg_u64 s[4:5], 0
	s_cselect_b64 s[6:7], -1, 0
	s_movk_i32 s4, 0x104
	v_mul_u32_u24_e32 v3, 0x104, v8
	v_lshl_add_u32 v0, v8, 2, 16
	v_mul_lo_u32 v1, v9, s4
	v_cndmask_b32_e64 v4, 0, 1, s[6:7]
	v_add_u32_e32 v18, v2, v3
	v_mov_b32_e32 v11, 0
	s_add_i32 s4, s2, 0xb80
	s_lshl_b32 s4, s4, 6
	s_lshl_b32 s5, s34, 6
	v_cmp_ne_u32_e64 s[14:15], 1, v4
	s_movk_i32 s6, 0x2000
	v_add_u32_e32 v13, v0, v1
	v_lshlrev_b32_e32 v10, 1, v8
	v_add_u32_e32 v19, 0x400, v18
	s_add_i32 s7, s2, 0xb80
	s_branch .LBB0_693

.Lgate_skip:
	s_cmp_lt_u32 s2, 64
	s_cbranch_scc1 .Lmv1_skip
	s_cmp_lt_u32 s2, 192
	s_cbranch_scc1 .Lmv1_clsB
	s_sub_i32 s60, s2, 192
	s_sub_i32 s61, s34, 192
	s_movk_i32 s64, 0x880
	s_branch .Lmv1_go
.Lmv1_clsB:
	s_add_i32 s60, s2, 0x840
	s_movk_i32 s61, 128
	s_movk_i32 s64, 0xb80
.Lmv1_go:
	v_mov_b32_e32 v0, v136
	v_readlane_b32 s4, v232, 21
	v_readlane_b32 s5, v232, 22
	v_readlane_b32 s6, v232, 23
	v_readlane_b32 s7, v232, 24
	s_nop 3
	v_ashrrev_i32_e32 v9, 3, v0
	v_lshlrev_b32_e32 v0, 3, v0
	v_and_b32_e32 v8, 56, v0
	v_lshl_add_u32 v2, v9, 2, 16
	s_waitcnt lgkmcnt(0)
	s_add_u32 s16, s6, 0x4000000
	s_addc_u32 s17, s7, 0
	s_add_u32 s18, s4, 0x2000
	s_addc_u32 s19, s5, 0
	s_add_u32 s20, s30, 0x2800000
	s_addc_u32 s21, s31, 0
	s_cmp_lg_u64 s[4:5], 0
	s_cselect_b64 s[6:7], -1, 0
	s_movk_i32 s4, 0x104
	v_mul_u32_u24_e32 v3, 0x104, v8
	v_lshl_add_u32 v0, v8, 2, 16
	v_mul_lo_u32 v1, v9, s4
	v_cndmask_b32_e64 v4, 0, 1, s[6:7]
	v_add_u32_e32 v18, v2, v3
	v_mov_b32_e32 v11, 0
	s_lshl_b32 s4, s60, 6
	s_lshl_b32 s5, s61, 6
	v_cmp_ne_u32_e64 s[14:15], 1, v4
	s_movk_i32 s6, 0x2000
	v_add_u32_e32 v13, v0, v1
	v_lshlrev_b32_e32 v10, 1, v8
	v_add_u32_e32 v19, 0x400, v18
	s_mov_b32 s7, s60
	s_branch .Lmv1_693
.Lmv1_692:
	s_or_b64 exec, exec, s[62:63]
	s_add_i32 s7, s7, s61
	s_add_i32 s4, s4, s5
	s_cmp_lt_i32 s7, s64
	s_barrier
	s_cbranch_scc0 .Lmv1_done
